# E29: E27 + mixer score tiles issue all eight bias-table LDS reads up front into free registers (no read-wait-add ladder of seven steps per tile)
# baseline (speedup 1.0000x reference)
; template <class MB> __device__ __forceinline__ void la_soft(LA& st, f32x16& s, const TP& t, bf16x8& pf0, bf16x8& pf1) {
;     float mx = NEGBIG;
; #pragma unroll
;     for (int r = 0; r < 16; ++r) { s[r] = MB::apply(t, r, s[r]); mx = __builtin_fmaxf(mx, s[r]); }
;     { auto rr = __builtin_amdgcn_permlane32_swap(__float_as_uint(mx), __float_as_uint(mx), false, false); mx = __builtin_fmaxf(__uint_as_float(rr[0]), __uint_as_float(rr[1])); }
;     if (__any(mx > st.m)) { const float mn = __builtin_fmaxf(st.m, mx), alpha = __builtin_amdgcn_exp2f(st.m - mn); st.m = mn; st.l *= alpha; st.o0 *= alpha; st.o1 *= alpha; }
; template <class MB, int V1, class VS> __device__ __forceinline__ void la_step2(LA& sa, LA& sb, const bf16x8 (&qa)[4], const bf16x8 (&qb)[4], Frag& f, const char* kb, const VS& vs, const TP& t, const TP& n) {
;     bf16x8 pa0, pa1;
;     { f32x16 s0 = zero16();
; #pragma unroll
;       for (int d0 = 0; d0 < 4; ++d0) s0 = __builtin_amdgcn_mfma_f32_32x32x16_bf16(f.k[d0], qa[d0], s0, 0, 0, 0);
;       la_soft<MB>(sa, s0, t, pa0, pa1); }
.LBB0_661:
	s_add_i32 s4, s7, s9
	s_addk_i32 s4, 0xffa0
	s_cmpk_lt_u32 s4, 0x4000
	v_lshl_add_u32 v64, v64, 1, v148
	s_cselect_b64 s[4:5], -1, 0
	s_cmpk_lg_i32 s9, 0xc0
	v_add_u32_e32 v65, 0x9000, v64
	s_cselect_b64 s[10:11], -1, 0
	ds_read_b128 v[136:139], v65 offset:41472
	ds_read_b128 v[128:131], v65 offset:41504
	ds_read_b128 v[140:143], v64 offset:36864
	ds_read_b128 v[132:135], v64 offset:36896
	s_and_b64 vcc, s[10:11], s[4:5]
	v_add_u32_e32 v150, 0x80, v152
	v_mov_b32_e32 v64, s53
	v_cndmask_b32_e32 v167, v64, v150, vcc
	ds_read2_b32 v[154:155], v167 offset1:1
	ds_read2_b32 v[234:235], v167 offset0:2 offset1:3
	ds_read2_b32 v[236:237], v167 offset0:4 offset1:5
	ds_read2_b32 v[238:239], v167 offset0:6 offset1:7
	ds_read2_b32 v[240:241], v167 offset0:16 offset1:17
	ds_read2_b32 v[242:243], v167 offset0:18 offset1:19
	ds_read2_b32 v[244:245], v167 offset0:20 offset1:21
	ds_read2_b32 v[246:247], v167 offset0:22 offset1:23
	s_waitcnt vmcnt(3)
	s_nop 0
	v_mfma_f32_32x32x16_bf16 v[64:79], v[124:127], v[96:99], 0
	s_waitcnt vmcnt(2)
	v_mfma_f32_32x32x16_bf16 v[64:79], v[120:123], v[88:91], v[64:79]
	s_waitcnt vmcnt(1)
	v_mfma_f32_32x32x16_bf16 v[64:79], v[116:119], v[92:95], v[64:79]
	s_waitcnt vmcnt(0)
	v_mfma_f32_32x32x16_bf16 v[64:79], v[112:115], v[100:103], v[64:79]
	s_waitcnt lgkmcnt(0)
	s_nop 10
	v_add_f32_e32 v154, v64, v154
	v_add_f32_e32 v153, v65, v155
	v_max3_f32 v157, v154, s2, v153
	v_add_f32_e32 v156, v66, v234
	v_add_f32_e32 v155, v67, v235
	v_max3_f32 v66, v157, v156, v155
	v_add_f32_e32 v158, v68, v236
	v_add_f32_e32 v157, v69, v237
	v_max3_f32 v66, v66, v158, v157
	v_add_f32_e32 v160, v70, v238
	v_add_f32_e32 v159, v71, v239
	v_max3_f32 v66, v66, v160, v159
	v_add_f32_e32 v162, v72, v240
	v_add_f32_e32 v161, v73, v241
	v_max3_f32 v66, v66, v162, v161
	v_add_f32_e32 v166, v74, v242
	v_add_f32_e32 v165, v75, v243
	v_max3_f32 v66, v66, v166, v165
	v_add_f32_e32 v164, v76, v244
	v_add_f32_e32 v163, v77, v245
	v_max3_f32 v66, v66, v164, v163
	v_add_f32_e32 v168, v78, v246
	v_add_f32_e32 v167, v79, v247
	v_max3_f32 v64, v66, v168, v167
	v_mov_b32_e32 v65, v64
	s_nop 1
	v_permlane32_swap_b32_e32 v64, v65
	v_max_f32_e32 v65, v65, v65
	v_max_f32_e32 v64, v64, v64
	v_max_f32_e32 v64, v64, v65
	v_cmp_gt_f32_e32 vcc, v64, v151
	s_cbranch_vccz .LBB0_663
	v_max_f32_e32 v64, v64, v64
	v_max_f32_e32 v65, v151, v151
	v_max_f32_e32 v65, v65, v64
	v_sub_f32_e32 v64, v151, v65
	v_exp_f32_e32 v64, v64
	v_mov_b32_e32 v151, v65
	v_mul_f32_e32 v147, v64, v147
	v_pk_mul_f32 v[46:47], v[64:65], v[46:47] op_sel_hi:[0,1]
	v_pk_mul_f32 v[44:45], v[64:65], v[44:45] op_sel_hi:[0,1]
	v_pk_mul_f32 v[42:43], v[64:65], v[42:43] op_sel_hi:[0,1]
	v_pk_mul_f32 v[40:41], v[64:65], v[40:41] op_sel_hi:[0,1]
	v_pk_mul_f32 v[38:39], v[64:65], v[38:39] op_sel_hi:[0,1]
	v_pk_mul_f32 v[36:37], v[64:65], v[36:37] op_sel_hi:[0,1]
	v_pk_mul_f32 v[34:35], v[64:65], v[34:35] op_sel_hi:[0,1]
	v_pk_mul_f32 v[32:33], v[64:65], v[32:33] op_sel_hi:[0,1]
	v_pk_mul_f32 v[62:63], v[64:65], v[62:63] op_sel_hi:[0,1]
	v_pk_mul_f32 v[60:61], v[64:65], v[60:61] op_sel_hi:[0,1]
	v_pk_mul_f32 v[58:59], v[64:65], v[58:59] op_sel_hi:[0,1]
	v_pk_mul_f32 v[56:57], v[64:65], v[56:57] op_sel_hi:[0,1]
	v_pk_mul_f32 v[54:55], v[64:65], v[54:55] op_sel_hi:[0,1]
	v_pk_mul_f32 v[52:53], v[64:65], v[52:53] op_sel_hi:[0,1]
	v_pk_mul_f32 v[50:51], v[64:65], v[50:51] op_sel_hi:[0,1]
	v_pk_mul_f32 v[48:49], v[64:65], v[48:49] op_sel_hi:[0,1]

; #define LAS __attribute__((address_space(3)))
; __host__ __device__ __forceinline__ int vt_off(int d, int p) { return (d >> 1) * VTPP + (p >> 5) * 64 + (d & 1) * 32 + (p & 31); }
; #define LA_RUN2(NT, TILE, MB, V1, KB, VS_) do { Frag f_; { const TP t0_ = TILE(0); la_loadK(f_, KB, t0_); (VS_).template load<V1>(f_, t0_.voff); } \
;     _Pragma("unroll 1") for (int i_ = 0; i_ < (NT); ++i_) { const TP t_ = TILE(i_); const TP n_ = TILE(i_ + 1 < (NT) ? i_ + 1 : i_); la_step2<MB, V1>(sa, sb, qa, qb, f_, KB, VS_, t_, n_); } } while (0)
; template <class MB, int V1, class VS> __device__ __forceinline__ void la_step2(LA& sa, LA& sb, const bf16x8 (&qa)[4], const bf16x8 (&qb)[4], Frag& f, const char* kb, const VS& vs, const TP& t, const TP& n) {
;     bf16x8 pa0, pa1;
;     { f32x16 s0 = zero16();
; #pragma unroll
;       for (int d0 = 0; d0 < 4; ++d0) s0 = __builtin_amdgcn_mfma_f32_32x32x16_bf16(f.k[d0], qa[d0], s0, 0, 0, 0);
;       la_soft<MB>(sa, s0, t, pa0, pa1); }
; __global__ void __launch_bounds__(NWAVES * 64, 2) mk_fwd(Args args) {
;     ...
;                 auto tile = [&](int i) -> TP { const int t0r = q0 - 128 + 32 * i; const bool ok = t0r >= 0 && t0r < SEQ; const int t0 = ok ? t0r : q0; TP t;
;                     t.koff = ((unsigned)(t0 + lam) * PP + kc) * 2u; t.voff = (unsigned)(vt_off(vd, t0 + 8 * hi) * 2);
;                     t.tp = (ok && i <= 8) ? (const LAS char*)(tabA + (TABA_C + t0 + 8 * hi - tqa)) : negp;
;                     t.tp2 = (ok && i >= 1) ? (const LAS char*)(tabA + (TABA_C + t0 + 8 * hi - tqb)) : negp; t.cb = 0; return t; };
;                 LA_RUN2(10, tile, MB_A, 32, PB, vs);
.LBB0_673:
	v_lshlrev_b32_e32 v64, 1, v73
	v_ashrrev_i32_e32 v65, 31, v64
	v_lshl_add_u64 v[64:65], s[6:7], 0, v[64:65]
	v_add_co_u32_e32 v66, vcc, s80, v64
	s_add_i32 s8, s11, s13
	s_nop 0
	v_addc_co_u32_e32 v67, vcc, 0, v65, vcc
	global_load_dwordx4 v[128:131], v[66:67], off offset:2080
	global_load_dwordx4 v[136:139], v[66:67], off offset:2048
	global_load_dwordx4 v[132:135], v[64:65], off offset:32
	global_load_dwordx4 v[140:143], v[64:65], off
	s_cmpk_lt_u32 s8, 0x4000
	s_cselect_b64 s[8:9], -1, 0
	s_cmpk_lg_i32 s12, 0x480
	s_cselect_b64 s[14:15], -1, 0
	v_add_u32_e32 v197, s12, v195
	s_and_b64 vcc, s[14:15], s[8:9]
	v_add_u32_e32 v64, 0x80, v197
	v_mov_b32_e32 v65, s53
	v_cndmask_b32_e32 v212, v65, v64, vcc
	ds_read2_b32 v[200:201], v212 offset1:1
	ds_read2_b32 v[234:235], v212 offset0:2 offset1:3
	ds_read2_b32 v[236:237], v212 offset0:4 offset1:5
	ds_read2_b32 v[238:239], v212 offset0:6 offset1:7
	ds_read2_b32 v[240:241], v212 offset0:16 offset1:17
	ds_read2_b32 v[242:243], v212 offset0:18 offset1:19
	ds_read2_b32 v[244:245], v212 offset0:20 offset1:21
	ds_read2_b32 v[246:247], v212 offset0:22 offset1:23
	s_waitcnt vmcnt(7)
	s_nop 0
	v_mfma_f32_32x32x16_bf16 v[64:79], v[124:127], v[80:83], 0
	s_waitcnt vmcnt(6)
	v_mfma_f32_32x32x16_bf16 v[64:79], v[120:123], v[84:87], v[64:79]
	s_waitcnt vmcnt(5)
	v_mfma_f32_32x32x16_bf16 v[64:79], v[116:119], v[96:99], v[64:79]
	s_waitcnt vmcnt(4)
	v_mfma_f32_32x32x16_bf16 v[64:79], v[112:115], v[100:103], v[64:79]
	s_waitcnt lgkmcnt(0)
	s_nop 10
	v_add_f32_e32 v199, v64, v200
	v_add_f32_e32 v198, v65, v201
	v_max3_f32 v202, v199, s2, v198
	v_add_f32_e32 v201, v66, v234
	v_add_f32_e32 v200, v67, v235
	v_max3_f32 v66, v202, v201, v200
	v_add_f32_e32 v203, v68, v236
	v_add_f32_e32 v202, v69, v237
	v_max3_f32 v66, v66, v203, v202
	v_add_f32_e32 v205, v70, v238
	v_add_f32_e32 v204, v71, v239
	v_max3_f32 v66, v66, v205, v204
	v_add_f32_e32 v207, v72, v240
	v_add_f32_e32 v206, v73, v241
	v_max3_f32 v66, v66, v207, v206
	v_add_f32_e32 v211, v74, v242
	v_add_f32_e32 v210, v75, v243
	v_max3_f32 v66, v66, v211, v210
	v_add_f32_e32 v209, v76, v244
	v_add_f32_e32 v208, v77, v245
	v_max3_f32 v66, v66, v209, v208
	v_add_f32_e32 v213, v78, v246
	v_add_f32_e32 v212, v79, v247
	v_max3_f32 v64, v66, v213, v212
	v_mov_b32_e32 v65, v64
	s_nop 1
	v_permlane32_swap_b32_e32 v64, v65
	v_max_f32_e32 v65, v65, v65
	v_max_f32_e32 v64, v64, v64
	v_max_f32_e32 v64, v64, v65
	v_cmp_gt_f32_e32 vcc, v64, v196
	s_cbranch_vccz .LBB0_675
	v_max_f32_e32 v64, v64, v64
	v_max_f32_e32 v65, v196, v196
	v_max_f32_e32 v65, v65, v64
	v_sub_f32_e32 v64, v196, v65
	v_exp_f32_e32 v64, v64
	v_mov_b32_e32 v196, v65
	v_mul_f32_e32 v193, v193, v64
	v_pk_mul_f32 v[62:63], v[62:63], v[64:65] op_sel_hi:[1,0]
	v_pk_mul_f32 v[60:61], v[60:61], v[64:65] op_sel_hi:[1,0]
	v_pk_mul_f32 v[58:59], v[58:59], v[64:65] op_sel_hi:[1,0]
	v_pk_mul_f32 v[56:57], v[56:57], v[64:65] op_sel_hi:[1,0]
	v_pk_mul_f32 v[54:55], v[54:55], v[64:65] op_sel_hi:[1,0]
	v_pk_mul_f32 v[52:53], v[52:53], v[64:65] op_sel_hi:[1,0]
	v_pk_mul_f32 v[50:51], v[50:51], v[64:65] op_sel_hi:[1,0]
	v_pk_mul_f32 v[48:49], v[48:49], v[64:65] op_sel_hi:[1,0]
	v_pk_mul_f32 v[46:47], v[46:47], v[64:65] op_sel_hi:[1,0]
	v_pk_mul_f32 v[44:45], v[44:45], v[64:65] op_sel_hi:[1,0]
	v_pk_mul_f32 v[42:43], v[42:43], v[64:65] op_sel_hi:[1,0]
	v_pk_mul_f32 v[40:41], v[40:41], v[64:65] op_sel_hi:[1,0]
	v_pk_mul_f32 v[38:39], v[38:39], v[64:65] op_sel_hi:[1,0]
	v_pk_mul_f32 v[36:37], v[36:37], v[64:65] op_sel_hi:[1,0]
	v_pk_mul_f32 v[34:35], v[34:35], v[64:65] op_sel_hi:[1,0]
	v_pk_mul_f32 v[32:33], v[32:33], v[64:65] op_sel_hi:[1,0]

; #define LAS __attribute__((address_space(3)))
; __host__ __device__ __forceinline__ int vt_off(int d, int p) { return (d >> 1) * VTPP + (p >> 5) * 64 + (d & 1) * 32 + (p & 31); }
; #define LA_RUN2(NT, TILE, MB, V1, KB, VS_) do { Frag f_; { const TP t0_ = TILE(0); la_loadK(f_, KB, t0_); (VS_).template load<V1>(f_, t0_.voff); } \
;     _Pragma("unroll 1") for (int i_ = 0; i_ < (NT); ++i_) { const TP t_ = TILE(i_); const TP n_ = TILE(i_ + 1 < (NT) ? i_ + 1 : i_); la_step2<MB, V1>(sa, sb, qa, qb, f_, KB, VS_, t_, n_); } } while (0)
; template <class MB, int V1, class VS> __device__ __forceinline__ void la_step2(LA& sa, LA& sb, const bf16x8 (&qa)[4], const bf16x8 (&qb)[4], Frag& f, const char* kb, const VS& vs, const TP& t, const TP& n) {
;     bf16x8 pa0, pa1;
;     { f32x16 s0 = zero16();
; #pragma unroll
;       for (int d0 = 0; d0 < 4; ++d0) s0 = __builtin_amdgcn_mfma_f32_32x32x16_bf16(f.k[d0], qa[d0], s0, 0, 0, 0);
;       la_soft<MB>(sa, s0, t, pa0, pa1); }
; __global__ void __launch_bounds__(NWAVES * 64, 2) mk_fwd(Args args) {
;     ...
;                 auto tile = [&](int i) -> TP { const int kr = rsa + i, krc = kr > 255 ? 255 : kr, t0 = 64 * krc + 32 * qh; const bool va = i <= 7, vb = kr >= rsb && kr < rsb + 8; TP t;
;                     t.koff = ((unsigned)(t0 + lam) * PP + kc) * 2u; t.voff = (unsigned)(vt_off(vd, t0 + 8 * hi) * 2);
;                     const LAS char* bp = bb0 + kr * 512;
;                     t.tp = va ? bp : negp; t.tp2 = vb ? bp - 512 : negp; t.cb = cbr; return t; };
;                 LA_RUN2(9, tile, MB_B, 32, PB, vs);
.LBB0_678:
	v_lshl_add_u32 v64, s41, 2, v165
	v_ashrrev_i32_e32 v65, 31, v64
	v_lshl_add_u64 v[64:65], s[56:57], 0, v[64:65]
	v_add_co_u32_e32 v66, vcc, s80, v64
	s_cmp_eq_u32 s60, 8
	s_nop 0
	v_addc_co_u32_e32 v67, vcc, 0, v65, vcc
	global_load_dwordx4 v[128:131], v[66:67], off offset:2080
	global_load_dwordx4 v[136:139], v[66:67], off offset:2048
	global_load_dwordx4 v[132:135], v[64:65], off offset:32
	global_load_dwordx4 v[140:143], v[64:65], off
	s_cselect_b64 s[40:41], -1, 0
	v_add_u32_e32 v166, 0x200, v167
	v_mov_b32_e32 v64, s53
	v_cndmask_b32_e64 v183, v166, v64, s[40:41]
	ds_read2_b32 v[168:169], v183 offset1:1
	ds_read2_b32 v[234:235], v183 offset0:2 offset1:3
	ds_read2_b32 v[236:237], v183 offset0:4 offset1:5
	ds_read2_b32 v[238:239], v183 offset0:6 offset1:7
	ds_read2_b32 v[240:241], v183 offset0:16 offset1:17
	ds_read2_b32 v[242:243], v183 offset0:18 offset1:19
	ds_read2_b32 v[244:245], v183 offset0:20 offset1:21
	ds_read2_b32 v[246:247], v183 offset0:22 offset1:23
	s_waitcnt vmcnt(7)
	s_nop 0
	v_mfma_f32_32x32x16_bf16 v[64:79], v[124:127], v[96:99], 0
	s_waitcnt vmcnt(6)
	v_mfma_f32_32x32x16_bf16 v[64:79], v[120:123], v[100:103], v[64:79]
	s_waitcnt vmcnt(5)
	v_mfma_f32_32x32x16_bf16 v[64:79], v[116:119], v[104:107], v[64:79]
	s_waitcnt vmcnt(4)
	v_mfma_f32_32x32x16_bf16 v[64:79], v[112:115], v[108:111], v[64:79]
	s_waitcnt lgkmcnt(0)
	s_nop 10
	v_add_f32_e32 v64, v64, v168
	v_cndmask_b32_e64 v168, v232, v64, s[6:7]
	v_add_f32_e32 v64, v65, v169
	v_cndmask_b32_e64 v169, v232, v64, s[8:9]
	v_max3_f32 v172, v168, s2, v169
	v_add_f32_e32 v64, v66, v234
	v_cndmask_b32_e64 v170, v232, v64, s[10:11]
	v_add_f32_e32 v64, v67, v235
	v_cndmask_b32_e64 v171, v232, v64, s[12:13]
	v_max3_f32 v66, v172, v170, v171
	v_add_f32_e32 v64, v68, v236
	v_cndmask_b32_e64 v172, v232, v64, s[14:15]
	v_add_f32_e32 v64, v69, v237
	v_cndmask_b32_e64 v173, v232, v64, s[16:17]
	v_max3_f32 v66, v66, v172, v173
	v_add_f32_e32 v64, v70, v238
	v_cndmask_b32_e64 v175, v232, v64, s[18:19]
	v_add_f32_e32 v64, v71, v239
	v_cndmask_b32_e64 v174, v232, v64, s[20:21]
	v_max3_f32 v66, v66, v175, v174
	v_add_f32_e32 v64, v72, v240
	v_cndmask_b32_e64 v176, v232, v64, s[22:23]
	v_add_f32_e32 v64, v73, v241
	v_cndmask_b32_e64 v177, v232, v64, s[24:25]
	v_max3_f32 v66, v66, v176, v177
	v_add_f32_e32 v64, v74, v242
	v_cndmask_b32_e64 v179, v232, v64, s[26:27]
	v_add_f32_e32 v64, v75, v243
	v_cndmask_b32_e64 v178, v232, v64, s[28:29]
	v_max3_f32 v66, v66, v179, v178
	v_add_f32_e32 v64, v76, v244
	v_cndmask_b32_e64 v180, v232, v64, s[30:31]
	v_add_f32_e32 v64, v77, v245
	v_cndmask_b32_e64 v182, v232, v64, s[34:35]
	v_max3_f32 v66, v66, v180, v182
	v_add_f32_e32 v64, v78, v246
	v_cndmask_b32_e64 v183, v232, v64, s[36:37]
	v_add_f32_e32 v64, v79, v247
	v_cndmask_b32_e64 v190, v232, v64, s[38:39]
	v_max3_f32 v64, v66, v183, v190
	v_mov_b32_e32 v65, v64
	s_nop 1
	v_permlane32_swap_b32_e32 v64, v65
	v_max_f32_e32 v65, v65, v65
	v_max_f32_e32 v64, v64, v64
	v_max_f32_e32 v64, v64, v65
	v_cmp_gt_f32_e32 vcc, v64, v162
	s_cbranch_vccz .LBB0_680
	v_max_f32_e32 v64, v64, v64
	v_max_f32_e32 v65, v162, v162
	v_max_f32_e32 v65, v65, v64
	v_sub_f32_e32 v64, v162, v65
	v_exp_f32_e32 v64, v64
	v_mov_b32_e32 v162, v65
	v_mul_f32_e32 v157, v157, v64
	v_pk_mul_f32 v[62:63], v[62:63], v[64:65] op_sel_hi:[1,0]
	v_pk_mul_f32 v[60:61], v[60:61], v[64:65] op_sel_hi:[1,0]
	v_pk_mul_f32 v[58:59], v[58:59], v[64:65] op_sel_hi:[1,0]
	v_pk_mul_f32 v[56:57], v[56:57], v[64:65] op_sel_hi:[1,0]
	v_pk_mul_f32 v[54:55], v[54:55], v[64:65] op_sel_hi:[1,0]
	v_pk_mul_f32 v[52:53], v[52:53], v[64:65] op_sel_hi:[1,0]
	v_pk_mul_f32 v[50:51], v[50:51], v[64:65] op_sel_hi:[1,0]
	v_pk_mul_f32 v[48:49], v[48:49], v[64:65] op_sel_hi:[1,0]
	v_pk_mul_f32 v[46:47], v[46:47], v[64:65] op_sel_hi:[1,0]
	v_pk_mul_f32 v[44:45], v[44:45], v[64:65] op_sel_hi:[1,0]
	v_pk_mul_f32 v[42:43], v[42:43], v[64:65] op_sel_hi:[1,0]
	v_pk_mul_f32 v[40:41], v[40:41], v[64:65] op_sel_hi:[1,0]
	v_pk_mul_f32 v[38:39], v[38:39], v[64:65] op_sel_hi:[1,0]
	v_pk_mul_f32 v[36:37], v[36:37], v[64:65] op_sel_hi:[1,0]
	v_pk_mul_f32 v[34:35], v[34:35], v[64:65] op_sel_hi:[1,0]
	v_pk_mul_f32 v[32:33], v[32:33], v[64:65] op_sel_hi:[1,0]

; __device__ __forceinline__ unsigned xb_ld(unsigned* p)              { return __hip_atomic_load(p, __ATOMIC_RELAXED, __HIP_MEMORY_SCOPE_AGENT); }
; __device__ __forceinline__ unsigned xb_add(unsigned* p, unsigned v) { return __hip_atomic_fetch_add(p, v, __ATOMIC_RELAXED, __HIP_MEMORY_SCOPE_AGENT); }
; #define XB_SPIN(cond, bar) do { unsigned _sp = 0; while (cond) { __builtin_amdgcn_s_sleep(1); \
;     if ((++_sp & 255u) == 0u) { if (xb_ld(&(bar)[XB_TMO])) break; if (_sp > XB_SPIN_CAP) { atomicAdd(&(bar)[XB_TMO], 1u); break; } } } } while (0)
; __device__ __forceinline__ unsigned xb_lane() { unsigned l = __builtin_amdgcn_mbcnt_hi(~0u, __builtin_amdgcn_mbcnt_lo(~0u, 0u)); asm volatile("" : "+v"(l)); return l; }
; __device__ __forceinline__ void xcd_barrier(const XcdBarrier& b) {
;     asm volatile("s_waitcnt vmcnt(0)" ::: "memory");
;     __syncthreads();
;     if (b.lead != 0u && xb_lane() == 0u) {
;         unsigned* bar = b.bar;
;         __builtin_amdgcn_s_waitcnt(0);
;         unsigned nloc = b.st[0], nx = b.st[1];
;         if (nloc == 0u) { xcd_barrier_complete(bar, b.x, nloc, nx); b.st[0] = nloc; b.st[1] = nx; }
;         const unsigned old = xb_add(&bar[XB_XSUB(b.x)], 1u);
;         const unsigned gen = old / nloc;
;         if (old + 1u == (gen + 1u) * nloc) {
;             __builtin_amdgcn_fence(__ATOMIC_RELEASE, "agent");
;             asm volatile("s_waitcnt vmcnt(0)" ::: "memory");
;             const unsigned og = xb_add(&bar[XB_TOP], 1u);
;             const unsigned tg = og / nx;
;             if (og + 1u == (tg + 1u) * nx) xb_add(&bar[XB_TOPGEN], 1u);
;             else XB_SPIN(xb_ld(&bar[XB_TOPGEN]) == tg, bar);
;             __builtin_amdgcn_fence(__ATOMIC_ACQUIRE, "agent");
;             xb_add(&bar[XB_XGEN(b.x)], 1u);
;             asm volatile("s_waitcnt vmcnt(0)" ::: "memory");
;         } else {
;             XB_SPIN(xb_ld(&bar[XB_XGEN(b.x)]) == gen, bar);
;             __builtin_amdgcn_fence(__ATOMIC_ACQUIRE, "agent");
;             asm volatile("s_waitcnt vmcnt(0)" ::: "memory");
;         }
;     }
;     __syncthreads();
; }
.LBB0_709:
	s_add_i32 s0, s36, 4
	s_cmp_lt_i32 s0, s51
	s_cselect_b64 s[4:5], -1, 0
	s_and_b64 s[6:7], s[46:47], s[4:5]
	s_andn2_b64 vcc, exec, s[6:7]
	s_cbranch_vccnz .LBB0_796
	v_readlane_b32 s8, v255, 3
	v_readlane_b32 s9, v255, 4
	s_mov_b64 s[6:7], -1
	s_and_b64 vcc, exec, s[8:9]
	s_cbranch_vccz .LBB0_783
	v_readfirstlane_b32 s6, v251
	v_readlane_b32 s1, v255, 2
	s_waitcnt vmcnt(0)
	s_cmp_eq_u32 s6, 0
	s_waitcnt vmcnt(0)
	s_barrier
	s_cbranch_scc1 .LBB0_782
	v_mov_b32_e32 v0, v252
	s_nop 0
	v_cmp_eq_u32_e32 vcc, 0, v0
	s_and_saveexec_b64 s[6:7], vcc
	s_cbranch_execz .LBB0_781
	v_readlane_b32 s8, v255, 26
	s_waitcnt vmcnt(0) expcnt(0) lgkmcnt(0)
	s_nop 0
	v_mov_b32_e32 v0, s8
	ds_read_b32 v2, v0
	v_readlane_b32 s8, v255, 27
	s_waitcnt lgkmcnt(0)
	v_cmp_ne_u32_e32 vcc, 0, v2
	v_mov_b32_e32 v0, s8
	ds_read_b32 v0, v0
	s_cbranch_vccnz .LBB0_745
	v_readlane_b32 s10, v255, 0
	v_readlane_b32 s11, v255, 1
	s_load_dwordx2 s[8:9], s[10:11], 0x4
	s_mov_b32 s15, 1
	s_waitcnt lgkmcnt(0)
	s_mul_i32 s14, s8, s3
	s_mul_i32 s14, s14, s9
	s_branch .LBB0_716
	s_nop 0
	s_nop 0
	s_nop 0
	s_nop 0
	s_nop 0
